# hyena in-proj epilogues (x1, x2|v): column-guard branches removed, per-column bias loads hoisted ahead of the store stream
# speedup vs baseline: 1.0089x; 1.0039x over previous
; template <bool SWAP, class Epi, bool THIN = false> ...
;     ...
;     for (int st = 0; st < ns; ++st) {
;       asm volatile("s_waitcnt vmcnt(0)" ::: "memory");
;       __builtin_amdgcn_s_barrier();
;       asm volatile("" ::: "memory");
;       if (st + 1 < ns) {
;         char* nb = smem + ((st + 1) & 1) * 65536;
;         const int ko = (st + 1) * 64;
; #pragma unroll
;         for (int i = 0; i < 4; ++i) { GLDS16(A + (size_t)(ap[i] + ko), nb + tid * 16 + i * 8192); GLDS16(Bt + (size_t)(bp[i] + ko), nb + 32768 + tid * 16 + i * 8192); }
;       }
;       const char* sa = smem + (st & 1) * 65536 + (wr * 64 + fr) * 128;
;       const char* sb = smem + (st & 1) * 65536 + 32768 + (wc * 128 + fr) * 128;
;       if constexpr (THIN) {
;         if (wc == 0) {
; #pragma unroll
;           for (int ks = 0; ks < 2; ++ks) {
;             bf16x8 af[4], bf[2];
; #pragma unroll
;             for (int m = 0; m < 4; ++m) af[m] = *(const bf16x8*)(sa + m * 2048 + (((ks * 4 + fq) ^ swz) << 4));
; #pragma unroll
;             for (int n = 0; n < 2; ++n) bf[n] = *(const bf16x8*)(sb + n * 2048 + (((ks * 4 + fq) ^ swz) << 4));
; #pragma unroll
;             for (int m = 0; m < 4; ++m)
; #pragma unroll
;               for (int n = 0; n < 2; ++n)
;                 acc[m][n] = SWAP ? __builtin_amdgcn_mfma_f32_16x16x32_bf16(bf[n], af[m], acc[m][n], 0, 0, 0)
;                                  : __builtin_amdgcn_mfma_f32_16x16x32_bf16(af[m], bf[n], acc[m][n], 0, 0, 0);
;           }
;         }
;       } else {
;       bf16x8 afA[4], afB[4], bfb[2][2];
; #pragma unroll
;       for (int m = 0; m < 4; ++m) afA[m] = *(const bf16x8*)(sa + m * 2048 + ((fq ^ swz) << 4));
; #pragma unroll
;       for (int n = 0; n < 2; ++n) bfb[0][n] = *(const bf16x8*)(sb + n * 2048 + ((fq ^ swz) << 4));
; #pragma unroll
;       for (int gq = 0; gq < 8; ++gq) {
;         const int ks = gq >> 2, nh = gq & 3;
;         if (gq < 7) {
;           const int ks2 = (gq + 1) >> 2, nh2 = (gq + 1) & 3;
; #pragma unroll
;           for (int n = 0; n < 2; ++n) bfb[(gq + 1) & 1][n] = *(const bf16x8*)(sb + (nh2 * 2 + n) * 2048 + (((ks2 * 4 + fq) ^ swz) << 4));
;         }
;         if (gq == 3) {
; #pragma unroll
;           for (int m = 0; m < 4; ++m) afB[m] = *(const bf16x8*)(sa + m * 2048 + (((4 + fq) ^ swz) << 4));
;         }
;         __builtin_amdgcn_sched_barrier(0);
; #pragma unroll
.LBB0_2643:
	s_add_i32 s8, s7, 0x10000
	s_and_b32 s9, s8, 0x10000
	v_add_u32_e32 v167, s9, v142
	s_nop 0
	v_readfirstlane_b32 s9, v167
	s_waitcnt vmcnt(0)
	s_barrier
	s_and_b32 s7, s7, 0x10000
	v_add_u32_e32 v130, s7, v143
	v_add_u32_e32 v167, v130, v145
	ds_read_b128 v[168:171], v167
	ds_read_b128 v[172:175], v167 offset:2048
	ds_read_b128 v[176:179], v167 offset:4096
	ds_read_b128 v[180:183], v167 offset:6144
	v_or_b32_e32 v167, s7, v144
	v_add_u32_e32 v204, v167, v145
	ds_read_b128 v[184:187], v204 offset:32768
	ds_read_b128 v[188:191], v204 offset:34816
	ds_read_b128 v[192:195], v204 offset:36864
	ds_read_b128 v[196:199], v204 offset:38912
	v_add_u32_e32 v130, v130, v146
	s_waitcnt lgkmcnt(3)
	v_mfma_f32_16x16x32_bf16 v[126:129], v[184:187], v[168:171], v[126:129]
	s_mov_b32 m0, s9
	v_mfma_f32_16x16x32_bf16 v[110:113], v[184:187], v[172:175], v[110:113]
	global_load_lds_dwordx4 v139, s[18:19]
	v_add_u32_e32 v139, 0x80, v139
	v_mfma_f32_16x16x32_bf16 v[82:85], v[184:187], v[176:179], v[82:85]
	v_mfma_f32_16x16x32_bf16 v[50:53], v[184:187], v[180:183], v[50:53]
	ds_read_b128 v[184:187], v204 offset:40960
	ds_read_b128 v[200:203], v204 offset:43008
	s_waitcnt lgkmcnt(4)
	v_mfma_f32_16x16x32_bf16 v[122:125], v[188:191], v[168:171], v[122:125]
	s_add_u32 m0, s9, 0x8000
	v_mfma_f32_16x16x32_bf16 v[106:109], v[188:191], v[172:175], v[106:109]
	global_load_lds_dwordx4 v138, s[24:25]
	v_add_u32_e32 v138, 0x80, v138
	v_mfma_f32_16x16x32_bf16 v[78:81], v[188:191], v[176:179], v[78:81]
	v_mfma_f32_16x16x32_bf16 v[42:45], v[188:191], v[180:183], v[42:45]
	s_waitcnt lgkmcnt(3)
	v_mfma_f32_16x16x32_bf16 v[118:121], v[192:195], v[168:171], v[118:121]
	s_add_u32 m0, s9, 0x2000
	v_mfma_f32_16x16x32_bf16 v[94:97], v[192:195], v[172:175], v[94:97]
	global_load_lds_dwordx4 v137, s[18:19]
	v_add_u32_e32 v137, 0x80, v137
	v_mfma_f32_16x16x32_bf16 v[58:61], v[192:195], v[176:179], v[58:61]
	v_mfma_f32_16x16x32_bf16 v[26:29], v[192:195], v[180:183], v[26:29]
	ds_read_b128 v[188:191], v204 offset:45056
	ds_read_b128 v[192:195], v204 offset:47104
	s_waitcnt lgkmcnt(4)
	v_mfma_f32_16x16x32_bf16 v[114:117], v[196:199], v[168:171], v[114:117]
	s_add_u32 m0, s9, 0xa000
	v_mfma_f32_16x16x32_bf16 v[86:89], v[196:199], v[172:175], v[86:89]
	global_load_lds_dwordx4 v136, s[24:25]
	v_add_u32_e32 v136, 0x80, v136
	v_mfma_f32_16x16x32_bf16 v[54:57], v[196:199], v[176:179], v[54:57]
	v_mfma_f32_16x16x32_bf16 v[22:25], v[196:199], v[180:183], v[22:25]
	v_add_u32_e32 v167, v167, v146
	s_waitcnt lgkmcnt(3)
	v_mfma_f32_16x16x32_bf16 v[102:105], v[184:187], v[168:171], v[102:105]
	ds_read_b128 v[196:199], v167 offset:32768
	ds_read_b128 v[204:207], v167 offset:34816
	s_add_u32 m0, s9, 0x4000
	v_mfma_f32_16x16x32_bf16 v[74:77], v[184:187], v[172:175], v[74:77]
	global_load_lds_dwordx4 v135, s[18:19]
	v_add_u32_e32 v135, 0x80, v135
	v_mfma_f32_16x16x32_bf16 v[46:49], v[184:187], v[176:179], v[46:49]
	v_mfma_f32_16x16x32_bf16 v[10:13], v[184:187], v[180:183], v[10:13]
	ds_read_b128 v[184:187], v130
	ds_read_b128 v[208:211], v130 offset:2048
	ds_read_b128 v[212:215], v130 offset:4096
	ds_read_b128 v[216:219], v130 offset:6144
	s_waitcnt lgkmcnt(8)
	v_mfma_f32_16x16x32_bf16 v[98:101], v[200:203], v[168:171], v[98:101]
	s_add_u32 m0, s9, 0xc000
	v_mfma_f32_16x16x32_bf16 v[66:69], v[200:203], v[172:175], v[66:69]
	global_load_lds_dwordx4 v134, s[24:25]
	v_add_u32_e32 v134, 0x80, v134
	v_mfma_f32_16x16x32_bf16 v[30:33], v[200:203], v[176:179], v[30:33]
	v_mfma_f32_16x16x32_bf16 v[6:9], v[200:203], v[180:183], v[6:9]
	s_waitcnt lgkmcnt(7)
	v_mfma_f32_16x16x32_bf16 v[70:73], v[188:191], v[168:171], v[70:73]
	s_add_u32 m0, s9, 0x6000
	s_waitcnt lgkmcnt(6)
	v_mfma_f32_16x16x32_bf16 v[62:65], v[192:195], v[168:171], v[62:65]
	global_load_lds_dwordx4 v133, s[18:19]
	v_add_u32_e32 v133, 0x80, v133
	v_mfma_f32_16x16x32_bf16 v[38:41], v[188:191], v[172:175], v[38:41]
	v_mfma_f32_16x16x32_bf16 v[34:37], v[192:195], v[172:175], v[34:37]
	ds_read_b128 v[168:171], v167 offset:36864
	ds_read_b128 v[172:175], v167 offset:38912
	v_mfma_f32_16x16x32_bf16 v[18:21], v[188:191], v[176:179], v[18:21]
	s_add_u32 m0, s9, 0xe000
	v_mfma_f32_16x16x32_bf16 v[14:17], v[192:195], v[176:179], v[14:17]
	global_load_lds_dwordx4 v132, s[24:25]
	v_add_u32_e32 v132, 0x80, v132
	v_mfma_f32_16x16x32_bf16 v[2:5], v[188:191], v[180:183], v[2:5]
	v_mfma_f32_16x16x32_bf16 v[90:93], v[192:195], v[180:183], v[90:93]
	ds_read_b128 v[176:179], v167 offset:40960
	ds_read_b128 v[180:183], v167 offset:43008
	s_waitcnt lgkmcnt(7)
	v_mfma_f32_16x16x32_bf16 v[126:129], v[196:199], v[184:187], v[126:129]
	v_mfma_f32_16x16x32_bf16 v[122:125], v[204:207], v[184:187], v[122:125]
	s_waitcnt lgkmcnt(6)
	v_mfma_f32_16x16x32_bf16 v[110:113], v[196:199], v[208:211], v[110:113]
	v_mfma_f32_16x16x32_bf16 v[106:109], v[204:207], v[208:211], v[106:109]
	s_waitcnt lgkmcnt(5)
	v_mfma_f32_16x16x32_bf16 v[82:85], v[196:199], v[212:215], v[82:85]
	v_mfma_f32_16x16x32_bf16 v[78:81], v[204:207], v[212:215], v[78:81]
	s_waitcnt lgkmcnt(4)
	v_mfma_f32_16x16x32_bf16 v[50:53], v[196:199], v[216:219], v[50:53]
	v_mfma_f32_16x16x32_bf16 v[42:45], v[204:207], v[216:219], v[42:45]
	s_waitcnt lgkmcnt(3)
	v_mfma_f32_16x16x32_bf16 v[118:121], v[168:171], v[184:187], v[118:121]
	v_mfma_f32_16x16x32_bf16 v[94:97], v[168:171], v[208:211], v[94:97]
	v_mfma_f32_16x16x32_bf16 v[58:61], v[168:171], v[212:215], v[58:61]
	v_mfma_f32_16x16x32_bf16 v[26:29], v[168:171], v[216:219], v[26:29]
	ds_read_b128 v[168:171], v167 offset:45056
	ds_read_b128 v[188:191], v167 offset:47104
	s_waitcnt lgkmcnt(4)
; template <bool SWAP, class Epi, bool THIN = false> ...
;     ...
;       for (int gq = 0; gq < 8; ++gq) {
;         const int ks = gq >> 2, nh = gq & 3;
;         if (gq < 7) {
;           const int ks2 = (gq + 1) >> 2, nh2 = (gq + 1) & 3;
; #pragma unroll
;           for (int n = 0; n < 2; ++n) bfb[(gq + 1) & 1][n] = *(const bf16x8*)(sb + (nh2 * 2 + n) * 2048 + (((ks2 * 4 + fq) ^ swz) << 4));
;         }
;         if (gq == 3) {
; #pragma unroll
;           for (int m = 0; m < 4; ++m) afB[m] = *(const bf16x8*)(sa + m * 2048 + (((4 + fq) ^ swz) << 4));
;         }
;         __builtin_amdgcn_sched_barrier(0);
; #pragma unroll
;         for (int m = 0; m < 4; ++m)
; #pragma unroll
;           for (int n = 0; n < 2; ++n) {
;             const bf16x8 av = ks ? afB[m] : afA[m];
;             acc[m][nh * 2 + n] = SWAP ? __builtin_amdgcn_mfma_f32_16x16x32_bf16(bfb[gq & 1][n], av, acc[m][nh * 2 + n], 0, 0, 0)
;                                       : __builtin_amdgcn_mfma_f32_16x16x32_bf16(av, bfb[gq & 1][n], acc[m][nh * 2 + n], 0, 0, 0);
;           }
;       }
;       }
;     }
;     __syncthreads();
	v_mfma_f32_16x16x32_bf16 v[114:117], v[172:175], v[184:187], v[114:117]
	v_mfma_f32_16x16x32_bf16 v[86:89], v[172:175], v[208:211], v[86:89]
	v_mfma_f32_16x16x32_bf16 v[54:57], v[172:175], v[212:215], v[54:57]
	v_mfma_f32_16x16x32_bf16 v[22:25], v[172:175], v[216:219], v[22:25]
	s_waitcnt lgkmcnt(3)
	v_mfma_f32_16x16x32_bf16 v[102:105], v[176:179], v[184:187], v[102:105]
	s_waitcnt lgkmcnt(2)
	v_mfma_f32_16x16x32_bf16 v[98:101], v[180:183], v[184:187], v[98:101]
	v_mfma_f32_16x16x32_bf16 v[74:77], v[176:179], v[208:211], v[74:77]
	v_mfma_f32_16x16x32_bf16 v[66:69], v[180:183], v[208:211], v[66:69]
	v_mfma_f32_16x16x32_bf16 v[46:49], v[176:179], v[212:215], v[46:49]
	v_mfma_f32_16x16x32_bf16 v[30:33], v[180:183], v[212:215], v[30:33]
	v_mfma_f32_16x16x32_bf16 v[10:13], v[176:179], v[216:219], v[10:13]
	v_mfma_f32_16x16x32_bf16 v[6:9], v[180:183], v[216:219], v[6:9]
	s_waitcnt lgkmcnt(1)
	v_mfma_f32_16x16x32_bf16 v[70:73], v[168:171], v[184:187], v[70:73]
	s_add_i32 s6, s6, 64
	s_cmpk_eq_i32 s6, 0x3c0
	s_mov_b32 s7, s8
	s_waitcnt lgkmcnt(0)
	v_mfma_f32_16x16x32_bf16 v[62:65], v[188:191], v[184:187], v[62:65]
	v_mfma_f32_16x16x32_bf16 v[38:41], v[168:171], v[208:211], v[38:41]
	v_mfma_f32_16x16x32_bf16 v[34:37], v[188:191], v[208:211], v[34:37]
	v_mfma_f32_16x16x32_bf16 v[18:21], v[168:171], v[212:215], v[18:21]
	v_mfma_f32_16x16x32_bf16 v[14:17], v[188:191], v[212:215], v[14:17]
	v_mfma_f32_16x16x32_bf16 v[2:5], v[168:171], v[216:219], v[2:5]
	v_mfma_f32_16x16x32_bf16 v[90:93], v[188:191], v[216:219], v[90:93]
	s_cbranch_scc0 .LBB0_2643
	s_waitcnt vmcnt(0)
	s_barrier
	v_add_u32_e32 v130, v157, v145
	ds_read_b128 v[132:135], v130
	ds_read_b128 v[136:139], v130 offset:2048
	ds_read_b128 v[168:171], v130 offset:4096
	ds_read_b128 v[172:175], v130 offset:6144
	v_add_u32_e32 v130, v158, v145
	ds_read_b128 v[176:179], v130
	ds_read_b128 v[180:183], v130 offset:2048
	ds_read_b128 v[184:187], v130 offset:4096
	ds_read_b128 v[188:191], v130 offset:6144
	s_waitcnt lgkmcnt(0)
	v_mfma_f32_16x16x32_bf16 v[126:129], v[176:179], v[132:135], v[126:129]
	v_mfma_f32_16x16x32_bf16 v[110:113], v[176:179], v[136:139], v[110:113]
	v_mfma_f32_16x16x32_bf16 v[82:85], v[176:179], v[168:171], v[82:85]
	v_mfma_f32_16x16x32_bf16 v[50:53], v[176:179], v[172:175], v[50:53]
	ds_read_b128 v[176:179], v130 offset:8192
	ds_read_b128 v[192:195], v130 offset:10240
	v_mfma_f32_16x16x32_bf16 v[122:125], v[180:183], v[132:135], v[122:125]
	v_mfma_f32_16x16x32_bf16 v[106:109], v[180:183], v[136:139], v[106:109]
	v_mfma_f32_16x16x32_bf16 v[78:81], v[180:183], v[168:171], v[78:81]
	v_mfma_f32_16x16x32_bf16 v[42:45], v[180:183], v[172:175], v[42:45]
	v_mfma_f32_16x16x32_bf16 v[118:121], v[184:187], v[132:135], v[118:121]
	v_mfma_f32_16x16x32_bf16 v[180:183], v[184:187], v[136:139], v[94:97]
	v_mfma_f32_16x16x32_bf16 v[200:203], v[184:187], v[168:171], v[58:61]
	v_mfma_f32_16x16x32_bf16 v[204:207], v[188:191], v[168:171], v[54:57]
	v_mfma_f32_16x16x32_bf16 v[184:187], v[184:187], v[172:175], v[26:29]
	s_nop 2
	ds_read_b128 v[26:29], v130 offset:12288
	ds_read_b128 v[54:57], v130 offset:14336
	v_mfma_f32_16x16x32_bf16 v[114:117], v[188:191], v[132:135], v[114:117]
	v_mfma_f32_16x16x32_bf16 v[196:199], v[188:191], v[136:139], v[86:89]
	v_mfma_f32_16x16x32_bf16 v[188:191], v[188:191], v[172:175], v[22:25]
	v_add_u32_e32 v130, v158, v146
	s_waitcnt lgkmcnt(0)
	v_mfma_f32_16x16x32_bf16 v[208:211], v[192:195], v[168:171], v[30:33]
	ds_read_b128 v[22:25], v130
	ds_read_b128 v[86:89], v130 offset:2048
	s_nop 0
	v_add_u32_e32 v30, v157, v146
	v_mfma_f32_16x16x32_bf16 v[102:105], v[176:179], v[132:135], v[102:105]
	v_mfma_f32_16x16x32_bf16 v[74:77], v[176:179], v[136:139], v[74:77]
	v_mfma_f32_16x16x32_bf16 v[46:49], v[176:179], v[168:171], v[46:49]
	v_mfma_f32_16x16x32_bf16 v[10:13], v[176:179], v[172:175], v[10:13]
	ds_read_b128 v[176:179], v30
	ds_read_b128 v[212:215], v30 offset:2048
	ds_read_b128 v[216:219], v30 offset:4096
	ds_read_b128 v[220:223], v30 offset:6144
	v_mfma_f32_16x16x32_bf16 v[98:101], v[192:195], v[132:135], v[98:101]
	v_mfma_f32_16x16x32_bf16 v[66:69], v[192:195], v[136:139], v[66:69]
	v_mfma_f32_16x16x32_bf16 v[6:9], v[192:195], v[172:175], v[6:9]
	v_mfma_f32_16x16x32_bf16 v[224:227], v[26:29], v[136:139], v[38:41]
	v_mfma_f32_16x16x32_bf16 v[34:37], v[54:57], v[136:139], v[34:37]
	v_mfma_f32_16x16x32_bf16 v[136:139], v[26:29], v[168:171], v[18:21]
	v_mfma_f32_16x16x32_bf16 v[168:171], v[54:57], v[168:171], v[14:17]
	s_nop 2
	ds_read_b128 v[14:17], v130 offset:4096
	ds_read_b128 v[18:21], v130 offset:6144
	v_mfma_f32_16x16x32_bf16 v[192:195], v[26:29], v[132:135], v[70:73]
	v_mfma_f32_16x16x32_bf16 v[132:135], v[54:57], v[132:135], v[62:65]
	v_mfma_f32_16x16x32_bf16 v[2:5], v[26:29], v[172:175], v[2:5]
	v_mfma_f32_16x16x32_bf16 v[172:175], v[54:57], v[172:175], v[90:93]
	ds_read_b128 v[228:231], v130 offset:8192
	ds_read_b128 v[232:235], v130 offset:10240
	s_waitcnt lgkmcnt(0)
	v_mfma_f32_16x16x32_bf16 v[126:129], v[22:25], v[176:179], v[126:129]
	v_mfma_f32_16x16x32_bf16 v[122:125], v[86:89], v[176:179], v[122:125]
	v_mfma_f32_16x16x32_bf16 v[94:97], v[22:25], v[212:215], v[110:113]
	v_mfma_f32_16x16x32_bf16 v[90:93], v[86:89], v[212:215], v[106:109]
	v_mfma_f32_16x16x32_bf16 v[62:65], v[22:25], v[216:219], v[82:85]
	v_mfma_f32_16x16x32_bf16 v[58:61], v[86:89], v[216:219], v[78:81]
	v_mfma_f32_16x16x32_bf16 v[30:33], v[22:25], v[220:223], v[50:53]
	v_mfma_f32_16x16x32_bf16 v[26:29], v[86:89], v[220:223], v[42:45]
	v_mfma_f32_16x16x32_bf16 v[86:89], v[14:17], v[212:215], v[180:183]
	v_mfma_f32_16x16x32_bf16 v[22:25], v[14:17], v[220:223], v[184:187]
	s_nop 1
	ds_read_b128 v[180:183], v130 offset:12288
	ds_read_b128 v[184:187], v130 offset:14336
	v_mfma_f32_16x16x32_bf16 v[118:121], v[14:17], v[176:179], v[118:121]
	v_mfma_f32_16x16x32_bf16 v[114:117], v[18:21], v[176:179], v[114:117]
	v_mfma_f32_16x16x32_bf16 v[82:85], v[18:21], v[212:215], v[196:199]
	v_mfma_f32_16x16x32_bf16 v[54:57], v[14:17], v[216:219], v[200:203]
	v_mfma_f32_16x16x32_bf16 v[50:53], v[18:21], v[216:219], v[204:207]
	v_mfma_f32_16x16x32_bf16 v[18:21], v[18:21], v[220:223], v[188:191]
	v_mfma_f32_16x16x32_bf16 v[110:113], v[228:231], v[176:179], v[102:105]
	v_mfma_f32_16x16x32_bf16 v[106:109], v[232:235], v[176:179], v[98:101]
	v_mfma_f32_16x16x32_bf16 v[78:81], v[228:231], v[212:215], v[74:77]
	v_mfma_f32_16x16x32_bf16 v[70:73], v[232:235], v[212:215], v[66:69]
	v_mfma_f32_16x16x32_bf16 v[46:49], v[228:231], v[216:219], v[46:49]
	v_mfma_f32_16x16x32_bf16 v[38:41], v[232:235], v[216:219], v[208:211]
	v_mfma_f32_16x16x32_bf16 v[14:17], v[228:231], v[220:223], v[10:13]
	v_mfma_f32_16x16x32_bf16 v[6:9], v[232:235], v[220:223], v[6:9]
	v_mov_b32_e32 v130, v1
	s_waitcnt vmcnt(0) lgkmcnt(0)
	s_barrier
; __device__ __forceinline__ unsigned pack2(float a, float b) { unsigned r; asm("v_cvt_pk_bf16_f32 %0, %1, %2" : "=v"(r) : "v"(a), "v"(b)); return r; }
;   __device__ __forceinline__ void c4(int g, int rig, int col, f32x4 v) const {
;     const size_t row = (size_t)g * 2048 + rig;
;     const f32x4 b4 = *(const f32x4*)(bias + col);
;     uint2 u; u.x = pack2(v[0] + b4[0], v[1] + b4[1]); u.y = pack2(v[2] + b4[2], v[3] + b4[3]);
;     *(uint2*)(out + row * ld + col) = u;
;   }
; template <bool SWAP, class Epi, bool THIN = false> ...
;     ...
;     if constexpr (Epi::KIND == 0) {
; #pragma unroll
;       for (int m = 0; m < 4; ++m) {
;         const int rig = rig0 + rw + m * 16 + fr_e;
;         if constexpr (Epi::ROWSUM) {
;           float ss = 0.f;
; #pragma unroll
;           for (int n = 0; n < 8; ++n) {
;             const int col = nt * 256 + wc_e * 128 + n * 16 + fq_e * 4;
;             if (col < N) ss += epi.c4(g, rig, col, acc[m][n]);
;           }
;           ss += __shfl_xor(ss, 16); ss += __shfl_xor(ss, 32);
;           if (fq_e == 0) epi.rowsum(g, rig, nt * 2 + wc_e, ss);
;         } else {
; #pragma unroll
;           for (int n = 0; n < 8; ++n) {
;             const int col = nt * 256 + wc_e * 128 + n * 16 + fq_e * 4;
;             if (col < N) epi.c4(g, rig, col, acc[m][n]);
;           }
;         }
	v_mfma_f32_16x16x32_bf16 v[102:105], v[180:183], v[176:179], v[192:195]
	v_ashrrev_i32_e32 v11, 8, v130
	v_add_u32_e32 v11, s5, v11
	v_ashrrev_i32_e32 v12, 31, v11
	v_lshrrev_b32_e32 v12, 28, v12
	v_add_u32_e32 v12, v11, v12
	v_mfma_f32_16x16x32_bf16 v[98:101], v[184:187], v[176:179], v[132:135]
	v_ashrrev_i32_e32 v176, 4, v12
	v_lshlrev_b32_e32 v12, 11, v176
	v_lshlrev_b32_e32 v11, 7, v11
	v_sub_u32_e32 v11, v11, v12
	v_lshrrev_b32_e32 v12, 1, v130
	v_and_b32_e32 v10, 15, v130
	v_and_b32_e32 v12, 64, v12
	v_or3_b32 v134, v11, v12, v10
	v_lshlrev_b32_e32 v10, 1, v130
	v_and_b32_e32 v132, 0x80, v10
	v_mfma_f32_16x16x32_bf16 v[10:13], v[180:183], v[220:223], v[2:5]
	v_ashrrev_i32_e32 v177, 31, v176
	v_ashrrev_i32_e32 v135, 31, v134
	s_nop 0
	v_lshrrev_b32_e32 v2, 2, v130
	v_and_b32_e32 v2, 12, v2
	v_mfma_f32_16x16x32_bf16 v[74:77], v[180:183], v[212:215], v[224:227]
	v_or3_b32 v132, v2, v132, s4
	v_cmp_gt_i32_e32 vcc, s31, v132
	v_ashrrev_i32_e32 v133, 31, v132
	v_mfma_f32_16x16x32_bf16 v[66:69], v[184:187], v[212:215], v[34:37]
	v_mfma_f32_16x16x32_bf16 v[42:45], v[180:183], v[216:219], v[136:139]
	v_mfma_f32_16x16x32_bf16 v[34:37], v[184:187], v[216:219], v[168:171]
	s_nop 1
	v_lshlrev_b64 v[136:137], 11, v[176:177]
	v_lshl_add_u64 v[138:139], v[136:137], 0, v[134:135]
	v_lshlrev_b64 v[138:139], 11, v[138:139]
	v_mfma_f32_16x16x32_bf16 v[2:5], v[184:187], v[220:223], v[172:175]
	v_lshl_add_u64 v[138:139], s[20:21], 0, v[138:139]
	v_lshl_add_u64 v[188:189], v[132:133], 2, s[22:23]
	global_load_dwordx4 v[196:199], v[188:189], off
	global_load_dwordx4 v[200:203], v[188:189], off offset:64
	global_load_dwordx4 v[204:207], v[188:189], off offset:128
	global_load_dwordx4 v[208:211], v[188:189], off offset:192
	global_load_dwordx4 v[228:231], v[188:189], off offset:256
	global_load_dwordx4 v[232:235], v[188:189], off offset:320
	global_load_dwordx4 v[236:239], v[188:189], off offset:384
	global_load_dwordx4 v[240:243], v[188:189], off offset:448
	s_waitcnt vmcnt(0)
	v_add_f32_e32 v126, v126, v196
	v_add_f32_e32 v127, v127, v197
	v_add_f32_e32 v128, v128, v198
	v_add_f32_e32 v129, v129, v199
	v_cvt_pk_bf16_f32 v126, v126, v127
	v_cvt_pk_bf16_f32 v127, v128, v129
	v_lshl_add_u64 v[128:129], v[132:133], 1, v[138:139]
	global_store_dwordx2 v[128:129], v[126:127], off
	v_or_b32_e32 v126, 16, v132
	v_add_f32_e32 v122, v122, v200
	v_add_f32_e32 v123, v123, v201
	v_add_f32_e32 v124, v124, v202
	v_add_f32_e32 v125, v125, v203
	v_cvt_pk_bf16_f32 v122, v122, v123
	v_cvt_pk_bf16_f32 v123, v124, v125
	v_lshl_add_u64 v[124:125], v[132:133], 1, v[138:139]
	global_store_dwordx2 v[124:125], v[122:123], off offset:32
	v_or_b32_e32 v122, 32, v132
	v_add_f32_e32 v118, v118, v204
	v_add_f32_e32 v119, v119, v205
	v_add_f32_e32 v120, v120, v206
	v_add_f32_e32 v121, v121, v207
	v_cvt_pk_bf16_f32 v118, v118, v119
	v_cvt_pk_bf16_f32 v119, v120, v121
	v_lshl_add_u64 v[120:121], v[132:133], 1, v[138:139]
	global_store_dwordx2 v[120:121], v[118:119], off offset:64
	v_or_b32_e32 v118, 48, v132
	v_add_f32_e32 v114, v114, v208
	v_add_f32_e32 v115, v115, v209
	v_add_f32_e32 v116, v116, v210
	v_add_f32_e32 v117, v117, v211
	v_cvt_pk_bf16_f32 v114, v114, v115
	v_cvt_pk_bf16_f32 v115, v116, v117
	v_lshl_add_u64 v[116:117], v[132:133], 1, v[138:139]
	global_store_dwordx2 v[116:117], v[114:115], off offset:96
	v_or_b32_e32 v114, 64, v132
	v_add_f32_e32 v110, v110, v228
	v_add_f32_e32 v111, v111, v229
	v_add_f32_e32 v112, v112, v230
	v_add_f32_e32 v113, v113, v231
	v_cvt_pk_bf16_f32 v110, v110, v111
	v_cvt_pk_bf16_f32 v111, v112, v113
	v_lshl_add_u64 v[112:113], v[132:133], 1, v[138:139]
	global_store_dwordx2 v[112:113], v[110:111], off offset:128
	v_or_b32_e32 v110, 0x50, v132
	v_add_f32_e32 v106, v106, v232
	v_add_f32_e32 v107, v107, v233
	v_add_f32_e32 v108, v108, v234
	v_add_f32_e32 v109, v109, v235
	v_cvt_pk_bf16_f32 v106, v106, v107
	v_cvt_pk_bf16_f32 v107, v108, v109
	v_lshl_add_u64 v[108:109], v[132:133], 1, v[138:139]
	global_store_dwordx2 v[108:109], v[106:107], off offset:160
	v_or_b32_e32 v106, 0x60, v132
	v_add_f32_e32 v102, v102, v236
	v_add_f32_e32 v103, v103, v237
	v_add_f32_e32 v104, v104, v238
	v_add_f32_e32 v105, v105, v239
	v_cvt_pk_bf16_f32 v102, v102, v103
	v_cvt_pk_bf16_f32 v103, v104, v105
	v_lshl_add_u64 v[104:105], v[132:133], 1, v[138:139]
	global_store_dwordx2 v[104:105], v[102:103], off offset:192
	v_or_b32_e32 v102, 0x70, v132
	v_add_f32_e32 v98, v98, v240
	v_add_f32_e32 v99, v99, v241
	v_add_f32_e32 v100, v100, v242
	v_add_f32_e32 v101, v101, v243
	v_cvt_pk_bf16_f32 v98, v98, v99
	v_cvt_pk_bf16_f32 v99, v100, v101
	v_lshl_add_u64 v[100:101], v[132:133], 1, v[138:139]
	global_store_dwordx2 v[100:101], v[98:99], off offset:224
	v_or_b32_e32 v98, 16, v134
	v_ashrrev_i32_e32 v99, 31, v98
	v_lshl_add_u64 v[98:99], v[136:137], 0, v[98:99]
	v_lshlrev_b64 v[98:99], 11, v[98:99]
	v_lshl_add_u64 v[98:99], s[20:21], 0, v[98:99]
	v_add_f32_e32 v94, v94, v196
	v_add_f32_e32 v95, v95, v197
	v_add_f32_e32 v96, v96, v198
	v_add_f32_e32 v97, v97, v199
	v_cvt_pk_bf16_f32 v94, v94, v95
	v_cvt_pk_bf16_f32 v95, v96, v97
	v_lshl_add_u64 v[96:97], v[132:133], 1, v[98:99]
	global_store_dwordx2 v[96:97], v[94:95], off
	v_add_f32_e32 v90, v90, v200
	v_add_f32_e32 v91, v91, v201
	v_add_f32_e32 v92, v92, v202
	v_add_f32_e32 v93, v93, v203
	v_cvt_pk_bf16_f32 v90, v90, v91
	v_cvt_pk_bf16_f32 v91, v92, v93
	v_lshl_add_u64 v[92:93], v[132:133], 1, v[98:99]
	global_store_dwordx2 v[92:93], v[90:91], off offset:32
	v_add_f32_e32 v86, v86, v204
	v_add_f32_e32 v87, v87, v205
	v_add_f32_e32 v88, v88, v206
	v_add_f32_e32 v89, v89, v207
	v_cvt_pk_bf16_f32 v86, v86, v87
	v_cvt_pk_bf16_f32 v87, v88, v89
; __device__ __forceinline__ unsigned pack2(float a, float b) { unsigned r; asm("v_cvt_pk_bf16_f32 %0, %1, %2" : "=v"(r) : "v"(a), "v"(b)); return r; }
;   __device__ __forceinline__ void c4(int g, int rig, int col, f32x4 v) const {
;     const size_t row = (size_t)g * 2048 + rig;
;     const f32x4 b4 = *(const f32x4*)(bias + col);
;     uint2 u; u.x = pack2(v[0] + b4[0], v[1] + b4[1]); u.y = pack2(v[2] + b4[2], v[3] + b4[3]);
;     *(uint2*)(out + row * ld + col) = u;
;   }
; template <bool SWAP, class Epi, bool THIN = false> ...
;     ...
;     if constexpr (Epi::KIND == 0) {
; #pragma unroll
;       for (int m = 0; m < 4; ++m) {
;         const int rig = rig0 + rw + m * 16 + fr_e;
;         if constexpr (Epi::ROWSUM) {
;           float ss = 0.f;
; #pragma unroll
;           for (int n = 0; n < 8; ++n) {
;             const int col = nt * 256 + wc_e * 128 + n * 16 + fq_e * 4;
;             if (col < N) ss += epi.c4(g, rig, col, acc[m][n]);
;           }
;           ss += __shfl_xor(ss, 16); ss += __shfl_xor(ss, 32);
;           if (fq_e == 0) epi.rowsum(g, rig, nt * 2 + wc_e, ss);
;         } else {
; #pragma unroll
;           for (int n = 0; n < 8; ++n) {
;             const int col = nt * 256 + wc_e * 128 + n * 16 + fq_e * 4;
;             if (col < N) epi.c4(g, rig, col, acc[m][n]);
;           }
;         }
	v_lshl_add_u64 v[88:89], v[132:133], 1, v[98:99]
	global_store_dwordx2 v[88:89], v[86:87], off offset:64
	v_add_f32_e32 v82, v82, v208
	v_add_f32_e32 v83, v83, v209
	v_add_f32_e32 v84, v84, v210
	v_add_f32_e32 v85, v85, v211
	v_cvt_pk_bf16_f32 v82, v82, v83
	v_cvt_pk_bf16_f32 v83, v84, v85
	v_lshl_add_u64 v[84:85], v[132:133], 1, v[98:99]
	global_store_dwordx2 v[84:85], v[82:83], off offset:96
	v_add_f32_e32 v78, v78, v228
	v_add_f32_e32 v79, v79, v229
	v_add_f32_e32 v80, v80, v230
	v_add_f32_e32 v81, v81, v231
	v_cvt_pk_bf16_f32 v78, v78, v79
	v_cvt_pk_bf16_f32 v79, v80, v81
	v_lshl_add_u64 v[80:81], v[132:133], 1, v[98:99]
	global_store_dwordx2 v[80:81], v[78:79], off offset:128
	v_add_f32_e32 v70, v70, v232
	v_add_f32_e32 v71, v71, v233
	v_add_f32_e32 v72, v72, v234
	v_add_f32_e32 v73, v73, v235
	v_cvt_pk_bf16_f32 v70, v70, v71
	v_cvt_pk_bf16_f32 v71, v72, v73
	v_lshl_add_u64 v[72:73], v[132:133], 1, v[98:99]
	global_store_dwordx2 v[72:73], v[70:71], off offset:160
	v_add_f32_e32 v70, v74, v236
	v_add_f32_e32 v71, v75, v237
	v_add_f32_e32 v72, v76, v238
	v_add_f32_e32 v73, v77, v239
	v_cvt_pk_bf16_f32 v70, v70, v71
	v_cvt_pk_bf16_f32 v71, v72, v73
	v_lshl_add_u64 v[72:73], v[132:133], 1, v[98:99]
	global_store_dwordx2 v[72:73], v[70:71], off offset:192
	v_add_f32_e32 v66, v66, v240
	v_add_f32_e32 v67, v67, v241
	v_add_f32_e32 v68, v68, v242
	v_add_f32_e32 v69, v69, v243
	v_cvt_pk_bf16_f32 v66, v66, v67
	v_cvt_pk_bf16_f32 v67, v68, v69
	v_lshl_add_u64 v[68:69], v[132:133], 1, v[98:99]
	global_store_dwordx2 v[68:69], v[66:67], off offset:224
	v_or_b32_e32 v66, 32, v134
	v_ashrrev_i32_e32 v67, 31, v66
	v_lshl_add_u64 v[66:67], v[136:137], 0, v[66:67]
	v_lshlrev_b64 v[66:67], 11, v[66:67]
	v_lshl_add_u64 v[66:67], s[20:21], 0, v[66:67]
	v_add_f32_e32 v62, v62, v196
	v_add_f32_e32 v63, v63, v197
	v_add_f32_e32 v64, v64, v198
	v_add_f32_e32 v65, v65, v199
	v_cvt_pk_bf16_f32 v62, v62, v63
	v_cvt_pk_bf16_f32 v63, v64, v65
	v_lshl_add_u64 v[64:65], v[132:133], 1, v[66:67]
	global_store_dwordx2 v[64:65], v[62:63], off
	v_add_f32_e32 v58, v58, v200
	v_add_f32_e32 v59, v59, v201
	v_add_f32_e32 v60, v60, v202
	v_add_f32_e32 v61, v61, v203
	v_cvt_pk_bf16_f32 v58, v58, v59
	v_cvt_pk_bf16_f32 v59, v60, v61
	v_lshl_add_u64 v[60:61], v[132:133], 1, v[66:67]
	global_store_dwordx2 v[60:61], v[58:59], off offset:32
	v_add_f32_e32 v54, v54, v204
	v_add_f32_e32 v55, v55, v205
	v_add_f32_e32 v56, v56, v206
	v_add_f32_e32 v57, v57, v207
	v_cvt_pk_bf16_f32 v54, v54, v55
	v_cvt_pk_bf16_f32 v55, v56, v57
	v_lshl_add_u64 v[56:57], v[132:133], 1, v[66:67]
	global_store_dwordx2 v[56:57], v[54:55], off offset:64
	v_add_f32_e32 v50, v50, v208
	v_add_f32_e32 v51, v51, v209
	v_add_f32_e32 v52, v52, v210
	v_add_f32_e32 v53, v53, v211
	v_cvt_pk_bf16_f32 v50, v50, v51
	v_cvt_pk_bf16_f32 v51, v52, v53
	v_lshl_add_u64 v[52:53], v[132:133], 1, v[66:67]
	global_store_dwordx2 v[52:53], v[50:51], off offset:96
	v_add_f32_e32 v46, v46, v228
	v_add_f32_e32 v47, v47, v229
	v_add_f32_e32 v48, v48, v230
	v_add_f32_e32 v49, v49, v231
	v_cvt_pk_bf16_f32 v46, v46, v47
	v_cvt_pk_bf16_f32 v47, v48, v49
	v_lshl_add_u64 v[48:49], v[132:133], 1, v[66:67]
	global_store_dwordx2 v[48:49], v[46:47], off offset:128
	v_add_f32_e32 v38, v38, v232
	v_add_f32_e32 v39, v39, v233
	v_add_f32_e32 v40, v40, v234
	v_add_f32_e32 v41, v41, v235
	v_cvt_pk_bf16_f32 v38, v38, v39
	v_cvt_pk_bf16_f32 v39, v40, v41
	v_lshl_add_u64 v[40:41], v[132:133], 1, v[66:67]
	global_store_dwordx2 v[40:41], v[38:39], off offset:160
	v_add_f32_e32 v38, v42, v236
	v_add_f32_e32 v39, v43, v237
	v_add_f32_e32 v40, v44, v238
	v_add_f32_e32 v41, v45, v239
	v_cvt_pk_bf16_f32 v38, v38, v39
	v_cvt_pk_bf16_f32 v39, v40, v41
	v_lshl_add_u64 v[40:41], v[132:133], 1, v[66:67]
	global_store_dwordx2 v[40:41], v[38:39], off offset:192
	v_add_f32_e32 v34, v34, v240
	v_add_f32_e32 v35, v35, v241
	v_add_f32_e32 v36, v36, v242
	v_add_f32_e32 v37, v37, v243
	v_cvt_pk_bf16_f32 v34, v34, v35
	v_cvt_pk_bf16_f32 v35, v36, v37
	v_lshl_add_u64 v[36:37], v[132:133], 1, v[66:67]
	global_store_dwordx2 v[36:37], v[34:35], off offset:224
	v_or_b32_e32 v34, 48, v134
	v_ashrrev_i32_e32 v35, 31, v34
	v_lshl_add_u64 v[34:35], v[136:137], 0, v[34:35]
	v_lshlrev_b64 v[34:35], 11, v[34:35]
	v_lshl_add_u64 v[34:35], s[20:21], 0, v[34:35]
	v_add_f32_e32 v30, v30, v196
	v_add_f32_e32 v31, v31, v197
	v_add_f32_e32 v32, v32, v198
	v_add_f32_e32 v33, v33, v199
	v_cvt_pk_bf16_f32 v30, v30, v31
	v_cvt_pk_bf16_f32 v31, v32, v33
	v_lshl_add_u64 v[32:33], v[132:133], 1, v[34:35]
	global_store_dwordx2 v[32:33], v[30:31], off
	v_add_f32_e32 v26, v26, v200
	v_add_f32_e32 v27, v27, v201
	v_add_f32_e32 v28, v28, v202
	v_add_f32_e32 v29, v29, v203
	v_cvt_pk_bf16_f32 v26, v26, v27
	v_cvt_pk_bf16_f32 v27, v28, v29
	v_lshl_add_u64 v[28:29], v[132:133], 1, v[34:35]
	global_store_dwordx2 v[28:29], v[26:27], off offset:32
	v_add_f32_e32 v22, v22, v204
	v_add_f32_e32 v23, v23, v205
	v_add_f32_e32 v24, v24, v206
	v_add_f32_e32 v25, v25, v207
	v_cvt_pk_bf16_f32 v22, v22, v23
	v_cvt_pk_bf16_f32 v23, v24, v25
	v_lshl_add_u64 v[24:25], v[132:133], 1, v[34:35]
	global_store_dwordx2 v[24:25], v[22:23], off offset:64
	v_add_f32_e32 v18, v18, v208
	v_add_f32_e32 v19, v19, v209
	v_add_f32_e32 v20, v20, v210
	v_add_f32_e32 v21, v21, v211
	v_cvt_pk_bf16_f32 v18, v18, v19
	v_cvt_pk_bf16_f32 v19, v20, v21
	v_lshl_add_u64 v[20:21], v[132:133], 1, v[34:35]
	global_store_dwordx2 v[20:21], v[18:19], off offset:96
	v_add_f32_e32 v14, v14, v228
	v_add_f32_e32 v15, v15, v229
	v_add_f32_e32 v16, v16, v230
	v_add_f32_e32 v17, v17, v231
	v_cvt_pk_bf16_f32 v14, v14, v15
	v_cvt_pk_bf16_f32 v15, v16, v17
	v_lshl_add_u64 v[16:17], v[132:133], 1, v[34:35]
	global_store_dwordx2 v[16:17], v[14:15], off offset:128
	v_add_f32_e32 v6, v6, v232
	v_add_f32_e32 v7, v7, v233
	v_add_f32_e32 v8, v8, v234
	v_add_f32_e32 v9, v9, v235
	v_cvt_pk_bf16_f32 v6, v6, v7
	v_cvt_pk_bf16_f32 v7, v8, v9
	v_lshl_add_u64 v[8:9], v[132:133], 1, v[34:35]
	global_store_dwordx2 v[8:9], v[6:7], off offset:160
	v_add_f32_e32 v6, v10, v236
	v_add_f32_e32 v7, v11, v237
	v_add_f32_e32 v8, v12, v238
	v_add_f32_e32 v9, v13, v239
	v_cvt_pk_bf16_f32 v6, v6, v7
	v_cvt_pk_bf16_f32 v7, v8, v9
	v_lshl_add_u64 v[8:9], v[132:133], 1, v[34:35]
	global_store_dwordx2 v[8:9], v[6:7], off offset:192
	v_add_f32_e32 v2, v2, v240
	v_add_f32_e32 v3, v3, v241
	v_add_f32_e32 v4, v4, v242
	v_add_f32_e32 v5, v5, v243
	v_cvt_pk_bf16_f32 v2, v2, v3
	v_cvt_pk_bf16_f32 v3, v4, v5
	v_lshl_add_u64 v[4:5], v[132:133], 1, v[34:35]
	global_store_dwordx2 v[4:5], v[2:3], off offset:224
	s_branch .LBB0_2641

; template <bool SWAP, class Epi, bool THIN = false> ...
;     ...
;     for (int st = 0; st < ns; ++st) {
;       asm volatile("s_waitcnt vmcnt(0)" ::: "memory");
;       __builtin_amdgcn_s_barrier();
;       asm volatile("" ::: "memory");
;       if (st + 1 < ns) {
;         char* nb = smem + ((st + 1) & 1) * 65536;
;         const int ko = (st + 1) * 64;
; #pragma unroll
;         for (int i = 0; i < 4; ++i) { GLDS16(A + (size_t)(ap[i] + ko), nb + tid * 16 + i * 8192); GLDS16(Bt + (size_t)(bp[i] + ko), nb + 32768 + tid * 16 + i * 8192); }
;       }
;       const char* sa = smem + (st & 1) * 65536 + (wr * 64 + fr) * 128;
;       const char* sb = smem + (st & 1) * 65536 + 32768 + (wc * 128 + fr) * 128;
;       if constexpr (THIN) {
;         if (wc == 0) {
; #pragma unroll
;           for (int ks = 0; ks < 2; ++ks) {
;             bf16x8 af[4], bf[2];
; #pragma unroll
;             for (int m = 0; m < 4; ++m) af[m] = *(const bf16x8*)(sa + m * 2048 + (((ks * 4 + fq) ^ swz) << 4));
; #pragma unroll
;             for (int n = 0; n < 2; ++n) bf[n] = *(const bf16x8*)(sb + n * 2048 + (((ks * 4 + fq) ^ swz) << 4));
; #pragma unroll
;             for (int m = 0; m < 4; ++m)
; #pragma unroll
;               for (int n = 0; n < 2; ++n)
;                 acc[m][n] = SWAP ? __builtin_amdgcn_mfma_f32_16x16x32_bf16(bf[n], af[m], acc[m][n], 0, 0, 0)
;                                  : __builtin_amdgcn_mfma_f32_16x16x32_bf16(af[m], bf[n], acc[m][n], 0, 0, 0);
;           }
;         }
;       } else {
;       bf16x8 afA[4], afB[4], bfb[2][2];
; #pragma unroll
;       for (int m = 0; m < 4; ++m) afA[m] = *(const bf16x8*)(sa + m * 2048 + ((fq ^ swz) << 4));
; #pragma unroll
;       for (int n = 0; n < 2; ++n) bfb[0][n] = *(const bf16x8*)(sb + n * 2048 + ((fq ^ swz) << 4));
; #pragma unroll
;       for (int gq = 0; gq < 8; ++gq) {
;         const int ks = gq >> 2, nh = gq & 3;
;         if (gq < 7) {
;           const int ks2 = (gq + 1) >> 2, nh2 = (gq + 1) & 3;
; #pragma unroll
;           for (int n = 0; n < 2; ++n) bfb[(gq + 1) & 1][n] = *(const bf16x8*)(sb + (nh2 * 2 + n) * 2048 + (((ks2 * 4 + fq) ^ swz) << 4));
;         }
;         if (gq == 3) {
; #pragma unroll
;           for (int m = 0; m < 4; ++m) afB[m] = *(const bf16x8*)(sa + m * 2048 + (((4 + fq) ^ swz) << 4));
;         }
;         __builtin_amdgcn_sched_barrier(0);
; #pragma unroll
.LBB0_2714:
	s_add_i32 s8, s7, 0x10000
	s_and_b32 s9, s8, 0x10000
	v_add_u32_e32 v167, s9, v138
	s_nop 0
	v_readfirstlane_b32 s9, v167
	s_waitcnt vmcnt(0)
	s_barrier
	s_and_b32 s7, s7, 0x10000
	v_add_u32_e32 v130, s7, v139
	v_add_u32_e32 v167, v130, v141
	ds_read_b128 v[168:171], v167
	ds_read_b128 v[172:175], v167 offset:2048
	ds_read_b128 v[176:179], v167 offset:4096
	ds_read_b128 v[180:183], v167 offset:6144
	v_or_b32_e32 v167, s7, v140
	v_add_u32_e32 v204, v167, v141
	ds_read_b128 v[184:187], v204 offset:32768
	ds_read_b128 v[188:191], v204 offset:34816
	ds_read_b128 v[192:195], v204 offset:36864
	ds_read_b128 v[196:199], v204 offset:38912
	v_add_u32_e32 v130, v130, v142
	s_waitcnt lgkmcnt(3)
	v_mfma_f32_16x16x32_bf16 v[126:129], v[168:171], v[184:187], v[126:129]
	s_mov_b32 m0, s9
	v_mfma_f32_16x16x32_bf16 v[110:113], v[172:175], v[184:187], v[110:113]
	global_load_lds_dwordx4 v166, s[18:19]
	v_add_u32_e32 v166, 0x80, v166
	v_mfma_f32_16x16x32_bf16 v[82:85], v[176:179], v[184:187], v[82:85]
	v_mfma_f32_16x16x32_bf16 v[50:53], v[180:183], v[184:187], v[50:53]
	ds_read_b128 v[184:187], v204 offset:40960
	ds_read_b128 v[200:203], v204 offset:43008
	s_waitcnt lgkmcnt(4)
	v_mfma_f32_16x16x32_bf16 v[122:125], v[168:171], v[188:191], v[122:125]
	s_add_u32 m0, s9, 0x8000
	v_mfma_f32_16x16x32_bf16 v[106:109], v[172:175], v[188:191], v[106:109]
	global_load_lds_dwordx4 v165, s[24:25]
	v_add_u32_e32 v165, 0x80, v165
	v_mfma_f32_16x16x32_bf16 v[78:81], v[176:179], v[188:191], v[78:81]
	v_mfma_f32_16x16x32_bf16 v[42:45], v[180:183], v[188:191], v[42:45]
	s_waitcnt lgkmcnt(3)
	v_mfma_f32_16x16x32_bf16 v[118:121], v[168:171], v[192:195], v[118:121]
	s_add_u32 m0, s9, 0x2000
	v_mfma_f32_16x16x32_bf16 v[94:97], v[172:175], v[192:195], v[94:97]
	global_load_lds_dwordx4 v164, s[18:19]
	v_add_u32_e32 v164, 0x80, v164
	v_mfma_f32_16x16x32_bf16 v[58:61], v[176:179], v[192:195], v[58:61]
	v_mfma_f32_16x16x32_bf16 v[26:29], v[180:183], v[192:195], v[26:29]
	ds_read_b128 v[188:191], v204 offset:45056
	ds_read_b128 v[192:195], v204 offset:47104
	s_waitcnt lgkmcnt(4)
	v_mfma_f32_16x16x32_bf16 v[114:117], v[168:171], v[196:199], v[114:117]
	s_add_u32 m0, s9, 0xa000
	v_mfma_f32_16x16x32_bf16 v[86:89], v[172:175], v[196:199], v[86:89]
	global_load_lds_dwordx4 v163, s[24:25]
	v_add_u32_e32 v163, 0x80, v163
	v_mfma_f32_16x16x32_bf16 v[54:57], v[176:179], v[196:199], v[54:57]
	v_mfma_f32_16x16x32_bf16 v[22:25], v[180:183], v[196:199], v[22:25]
	v_add_u32_e32 v167, v167, v142
	s_waitcnt lgkmcnt(3)
	v_mfma_f32_16x16x32_bf16 v[102:105], v[168:171], v[184:187], v[102:105]
	ds_read_b128 v[196:199], v167 offset:32768
	ds_read_b128 v[204:207], v167 offset:34816
	s_add_u32 m0, s9, 0x4000
	v_mfma_f32_16x16x32_bf16 v[74:77], v[172:175], v[184:187], v[74:77]
	global_load_lds_dwordx4 v135, s[18:19]
	v_add_u32_e32 v135, 0x80, v135
	v_mfma_f32_16x16x32_bf16 v[46:49], v[176:179], v[184:187], v[46:49]
	v_mfma_f32_16x16x32_bf16 v[10:13], v[180:183], v[184:187], v[10:13]
	ds_read_b128 v[184:187], v130
	ds_read_b128 v[208:211], v130 offset:2048
	ds_read_b128 v[212:215], v130 offset:4096
	ds_read_b128 v[216:219], v130 offset:6144
	s_waitcnt lgkmcnt(8)
	v_mfma_f32_16x16x32_bf16 v[98:101], v[168:171], v[200:203], v[98:101]
	s_add_u32 m0, s9, 0xc000
	v_mfma_f32_16x16x32_bf16 v[66:69], v[172:175], v[200:203], v[66:69]
	global_load_lds_dwordx4 v134, s[24:25]
	v_add_u32_e32 v134, 0x80, v134
	v_mfma_f32_16x16x32_bf16 v[30:33], v[176:179], v[200:203], v[30:33]
	v_mfma_f32_16x16x32_bf16 v[6:9], v[180:183], v[200:203], v[6:9]
	s_waitcnt lgkmcnt(7)
	v_mfma_f32_16x16x32_bf16 v[70:73], v[168:171], v[188:191], v[70:73]
	s_add_u32 m0, s9, 0x6000
	s_waitcnt lgkmcnt(6)
	v_mfma_f32_16x16x32_bf16 v[62:65], v[168:171], v[192:195], v[62:65]
	global_load_lds_dwordx4 v133, s[18:19]
	v_add_u32_e32 v133, 0x80, v133
	v_mfma_f32_16x16x32_bf16 v[38:41], v[172:175], v[188:191], v[38:41]
	v_mfma_f32_16x16x32_bf16 v[34:37], v[172:175], v[192:195], v[34:37]
	ds_read_b128 v[168:171], v167 offset:36864
	ds_read_b128 v[172:175], v167 offset:38912
	v_mfma_f32_16x16x32_bf16 v[18:21], v[176:179], v[188:191], v[18:21]
	s_add_u32 m0, s9, 0xe000
	v_mfma_f32_16x16x32_bf16 v[14:17], v[176:179], v[192:195], v[14:17]
	global_load_lds_dwordx4 v132, s[24:25]
	v_add_u32_e32 v132, 0x80, v132
	v_mfma_f32_16x16x32_bf16 v[2:5], v[180:183], v[188:191], v[2:5]
	v_mfma_f32_16x16x32_bf16 v[90:93], v[180:183], v[192:195], v[90:93]
	ds_read_b128 v[176:179], v167 offset:40960
	ds_read_b128 v[180:183], v167 offset:43008
	s_waitcnt lgkmcnt(7)
	v_mfma_f32_16x16x32_bf16 v[126:129], v[184:187], v[196:199], v[126:129]
	v_mfma_f32_16x16x32_bf16 v[122:125], v[184:187], v[204:207], v[122:125]
	s_waitcnt lgkmcnt(6)
	v_mfma_f32_16x16x32_bf16 v[110:113], v[208:211], v[196:199], v[110:113]
	v_mfma_f32_16x16x32_bf16 v[106:109], v[208:211], v[204:207], v[106:109]
	s_waitcnt lgkmcnt(5)
	v_mfma_f32_16x16x32_bf16 v[82:85], v[212:215], v[196:199], v[82:85]
	v_mfma_f32_16x16x32_bf16 v[78:81], v[212:215], v[204:207], v[78:81]
	s_waitcnt lgkmcnt(4)
	v_mfma_f32_16x16x32_bf16 v[50:53], v[216:219], v[196:199], v[50:53]
	v_mfma_f32_16x16x32_bf16 v[42:45], v[216:219], v[204:207], v[42:45]
	s_waitcnt lgkmcnt(3)
	v_mfma_f32_16x16x32_bf16 v[118:121], v[184:187], v[168:171], v[118:121]
	v_mfma_f32_16x16x32_bf16 v[94:97], v[208:211], v[168:171], v[94:97]
	v_mfma_f32_16x16x32_bf16 v[58:61], v[212:215], v[168:171], v[58:61]
	v_mfma_f32_16x16x32_bf16 v[26:29], v[216:219], v[168:171], v[26:29]
	ds_read_b128 v[168:171], v167 offset:45056
	ds_read_b128 v[188:191], v167 offset:47104
	s_waitcnt lgkmcnt(4)
; template <bool SWAP, class Epi, bool THIN = false> ...
;     ...
;       for (int gq = 0; gq < 8; ++gq) {
;         const int ks = gq >> 2, nh = gq & 3;
;         if (gq < 7) {
;           const int ks2 = (gq + 1) >> 2, nh2 = (gq + 1) & 3;
; #pragma unroll
;           for (int n = 0; n < 2; ++n) bfb[(gq + 1) & 1][n] = *(const bf16x8*)(sb + (nh2 * 2 + n) * 2048 + (((ks2 * 4 + fq) ^ swz) << 4));
;         }
;         if (gq == 3) {
; #pragma unroll
;           for (int m = 0; m < 4; ++m) afB[m] = *(const bf16x8*)(sa + m * 2048 + (((4 + fq) ^ swz) << 4));
;         }
;         __builtin_amdgcn_sched_barrier(0);
; #pragma unroll
;         for (int m = 0; m < 4; ++m)
; #pragma unroll
;           for (int n = 0; n < 2; ++n) {
;             const bf16x8 av = ks ? afB[m] : afA[m];
;             acc[m][nh * 2 + n] = SWAP ? __builtin_amdgcn_mfma_f32_16x16x32_bf16(bfb[gq & 1][n], av, acc[m][nh * 2 + n], 0, 0, 0)
;                                       : __builtin_amdgcn_mfma_f32_16x16x32_bf16(av, bfb[gq & 1][n], acc[m][nh * 2 + n], 0, 0, 0);
;           }
;       }
;       }
;     }
;     __syncthreads();
	v_mfma_f32_16x16x32_bf16 v[114:117], v[184:187], v[172:175], v[114:117]
	v_mfma_f32_16x16x32_bf16 v[86:89], v[208:211], v[172:175], v[86:89]
	v_mfma_f32_16x16x32_bf16 v[54:57], v[212:215], v[172:175], v[54:57]
	v_mfma_f32_16x16x32_bf16 v[22:25], v[216:219], v[172:175], v[22:25]
	s_waitcnt lgkmcnt(3)
	v_mfma_f32_16x16x32_bf16 v[102:105], v[184:187], v[176:179], v[102:105]
	s_waitcnt lgkmcnt(2)
	v_mfma_f32_16x16x32_bf16 v[98:101], v[184:187], v[180:183], v[98:101]
	v_mfma_f32_16x16x32_bf16 v[74:77], v[208:211], v[176:179], v[74:77]
	v_mfma_f32_16x16x32_bf16 v[66:69], v[208:211], v[180:183], v[66:69]
	v_mfma_f32_16x16x32_bf16 v[46:49], v[212:215], v[176:179], v[46:49]
	v_mfma_f32_16x16x32_bf16 v[30:33], v[212:215], v[180:183], v[30:33]
	v_mfma_f32_16x16x32_bf16 v[10:13], v[216:219], v[176:179], v[10:13]
	v_mfma_f32_16x16x32_bf16 v[6:9], v[216:219], v[180:183], v[6:9]
	s_waitcnt lgkmcnt(1)
	v_mfma_f32_16x16x32_bf16 v[70:73], v[184:187], v[168:171], v[70:73]
	s_add_i32 s6, s6, 64
	s_cmpk_eq_i32 s6, 0x3c0
	s_mov_b32 s7, s8
	s_waitcnt lgkmcnt(0)
	v_mfma_f32_16x16x32_bf16 v[62:65], v[184:187], v[188:191], v[62:65]
	v_mfma_f32_16x16x32_bf16 v[38:41], v[208:211], v[168:171], v[38:41]
	v_mfma_f32_16x16x32_bf16 v[34:37], v[208:211], v[188:191], v[34:37]
	v_mfma_f32_16x16x32_bf16 v[18:21], v[212:215], v[168:171], v[18:21]
	v_mfma_f32_16x16x32_bf16 v[14:17], v[212:215], v[188:191], v[14:17]
	v_mfma_f32_16x16x32_bf16 v[2:5], v[216:219], v[168:171], v[2:5]
	v_mfma_f32_16x16x32_bf16 v[90:93], v[216:219], v[188:191], v[90:93]
	s_cbranch_scc0 .LBB0_2714
	s_waitcnt vmcnt(0)
	s_barrier
	v_add_u32_e32 v130, v153, v141
	ds_read_b128 v[132:135], v130
	ds_read_b128 v[164:167], v130 offset:2048
	ds_read_b128 v[168:171], v130 offset:4096
	ds_read_b128 v[172:175], v130 offset:6144
	v_add_u32_e32 v130, v154, v141
	ds_read_b128 v[176:179], v130
	ds_read_b128 v[180:183], v130 offset:2048
	ds_read_b128 v[184:187], v130 offset:4096
	ds_read_b128 v[188:191], v130 offset:6144
	s_waitcnt lgkmcnt(0)
	v_mfma_f32_16x16x32_bf16 v[126:129], v[132:135], v[176:179], v[126:129]
	v_mfma_f32_16x16x32_bf16 v[110:113], v[164:167], v[176:179], v[110:113]
	v_mfma_f32_16x16x32_bf16 v[82:85], v[168:171], v[176:179], v[82:85]
	v_mfma_f32_16x16x32_bf16 v[50:53], v[172:175], v[176:179], v[50:53]
	ds_read_b128 v[176:179], v130 offset:8192
	ds_read_b128 v[192:195], v130 offset:10240
	v_mfma_f32_16x16x32_bf16 v[122:125], v[132:135], v[180:183], v[122:125]
	v_mfma_f32_16x16x32_bf16 v[106:109], v[164:167], v[180:183], v[106:109]
	v_mfma_f32_16x16x32_bf16 v[78:81], v[168:171], v[180:183], v[78:81]
	v_mfma_f32_16x16x32_bf16 v[42:45], v[172:175], v[180:183], v[42:45]
	v_mfma_f32_16x16x32_bf16 v[118:121], v[132:135], v[184:187], v[118:121]
	v_mfma_f32_16x16x32_bf16 v[180:183], v[164:167], v[184:187], v[94:97]
	v_mfma_f32_16x16x32_bf16 v[200:203], v[168:171], v[184:187], v[58:61]
	v_mfma_f32_16x16x32_bf16 v[204:207], v[168:171], v[188:191], v[54:57]
	v_mfma_f32_16x16x32_bf16 v[184:187], v[172:175], v[184:187], v[26:29]
	s_nop 2
	ds_read_b128 v[26:29], v130 offset:12288
	ds_read_b128 v[54:57], v130 offset:14336
	v_mfma_f32_16x16x32_bf16 v[114:117], v[132:135], v[188:191], v[114:117]
	v_mfma_f32_16x16x32_bf16 v[196:199], v[164:167], v[188:191], v[86:89]
	v_mfma_f32_16x16x32_bf16 v[188:191], v[172:175], v[188:191], v[22:25]
	v_add_u32_e32 v130, v154, v142
	s_waitcnt lgkmcnt(0)
	v_mfma_f32_16x16x32_bf16 v[208:211], v[168:171], v[192:195], v[30:33]
	ds_read_b128 v[22:25], v130
	ds_read_b128 v[86:89], v130 offset:2048
	s_nop 0
	v_add_u32_e32 v30, v153, v142
	v_mfma_f32_16x16x32_bf16 v[102:105], v[132:135], v[176:179], v[102:105]
	v_mfma_f32_16x16x32_bf16 v[74:77], v[164:167], v[176:179], v[74:77]
	v_mfma_f32_16x16x32_bf16 v[46:49], v[168:171], v[176:179], v[46:49]
	v_mfma_f32_16x16x32_bf16 v[10:13], v[172:175], v[176:179], v[10:13]
	ds_read_b128 v[176:179], v30
	ds_read_b128 v[212:215], v30 offset:2048
	ds_read_b128 v[216:219], v30 offset:4096
	ds_read_b128 v[220:223], v30 offset:6144
	v_mfma_f32_16x16x32_bf16 v[98:101], v[132:135], v[192:195], v[98:101]
	v_mfma_f32_16x16x32_bf16 v[66:69], v[164:167], v[192:195], v[66:69]
	v_mfma_f32_16x16x32_bf16 v[6:9], v[172:175], v[192:195], v[6:9]
	v_mfma_f32_16x16x32_bf16 v[192:195], v[164:167], v[26:29], v[38:41]
	v_mfma_f32_16x16x32_bf16 v[34:37], v[164:167], v[54:57], v[34:37]
	v_mfma_f32_16x16x32_bf16 v[164:167], v[168:171], v[26:29], v[18:21]
	v_mfma_f32_16x16x32_bf16 v[168:171], v[168:171], v[54:57], v[14:17]
	s_nop 2
	ds_read_b128 v[14:17], v130 offset:4096
	ds_read_b128 v[18:21], v130 offset:6144
	v_mfma_f32_16x16x32_bf16 v[70:73], v[132:135], v[26:29], v[70:73]
	v_mfma_f32_16x16x32_bf16 v[132:135], v[132:135], v[54:57], v[62:65]
	v_mfma_f32_16x16x32_bf16 v[2:5], v[172:175], v[26:29], v[2:5]
	v_mfma_f32_16x16x32_bf16 v[172:175], v[172:175], v[54:57], v[90:93]
	ds_read_b128 v[224:227], v130 offset:8192
	ds_read_b128 v[228:231], v130 offset:10240
	s_waitcnt lgkmcnt(0)
	v_mfma_f32_16x16x32_bf16 v[126:129], v[176:179], v[22:25], v[126:129]
	v_mfma_f32_16x16x32_bf16 v[122:125], v[176:179], v[86:89], v[122:125]
	v_mfma_f32_16x16x32_bf16 v[94:97], v[212:215], v[22:25], v[110:113]
	v_mfma_f32_16x16x32_bf16 v[90:93], v[212:215], v[86:89], v[106:109]
	v_mfma_f32_16x16x32_bf16 v[62:65], v[216:219], v[22:25], v[82:85]
	v_mfma_f32_16x16x32_bf16 v[58:61], v[216:219], v[86:89], v[78:81]
	v_mfma_f32_16x16x32_bf16 v[30:33], v[220:223], v[22:25], v[50:53]
	v_mfma_f32_16x16x32_bf16 v[26:29], v[220:223], v[86:89], v[42:45]
	v_mfma_f32_16x16x32_bf16 v[86:89], v[212:215], v[14:17], v[180:183]
	v_mfma_f32_16x16x32_bf16 v[22:25], v[220:223], v[14:17], v[184:187]
	s_nop 1
	ds_read_b128 v[180:183], v130 offset:12288
	ds_read_b128 v[184:187], v130 offset:14336
	v_mfma_f32_16x16x32_bf16 v[118:121], v[176:179], v[14:17], v[118:121]
	v_mfma_f32_16x16x32_bf16 v[114:117], v[176:179], v[18:21], v[114:117]
	v_mfma_f32_16x16x32_bf16 v[82:85], v[212:215], v[18:21], v[196:199]
	v_mfma_f32_16x16x32_bf16 v[54:57], v[216:219], v[14:17], v[200:203]
	v_mfma_f32_16x16x32_bf16 v[50:53], v[216:219], v[18:21], v[204:207]
	v_mfma_f32_16x16x32_bf16 v[18:21], v[220:223], v[18:21], v[188:191]
	v_mfma_f32_16x16x32_bf16 v[110:113], v[176:179], v[224:227], v[102:105]
	v_mfma_f32_16x16x32_bf16 v[106:109], v[176:179], v[228:231], v[98:101]
	v_mfma_f32_16x16x32_bf16 v[78:81], v[212:215], v[224:227], v[74:77]
	v_mfma_f32_16x16x32_bf16 v[74:77], v[212:215], v[228:231], v[66:69]
	v_mfma_f32_16x16x32_bf16 v[46:49], v[216:219], v[224:227], v[46:49]
	v_mfma_f32_16x16x32_bf16 v[38:41], v[216:219], v[228:231], v[208:211]
	v_mfma_f32_16x16x32_bf16 v[14:17], v[220:223], v[224:227], v[10:13]
	v_mfma_f32_16x16x32_bf16 v[6:9], v[220:223], v[228:231], v[6:9]
	v_mov_b32_e32 v130, v1
	s_waitcnt vmcnt(0) lgkmcnt(0)
	s_barrier
; __device__ __forceinline__ unsigned pack2(float a, float b) { unsigned r; asm("v_cvt_pk_bf16_f32 %0, %1, %2" : "=v"(r) : "v"(a), "v"(b)); return r; }
;   __device__ __forceinline__ void r4(int g, int rig, int col, f32x4 v) const {
;     const float b = bias[col];
;     uint2 u; u.x = pack2(v[0] + b, v[1] + b); u.y = pack2(v[2] + b, v[3] + b);
;     *(uint2*)(out + (size_t)col * 16384 + (size_t)g * 2048 + rig) = u;
;   }
; template <bool SWAP, class Epi, bool THIN = false> ...
;     ...
;     } else if constexpr (Epi::KIND == 1) {
; #pragma unroll
;       for (int m = 0; m < 4; ++m) {
;         const int rig = rig0 + rw + m * 16 + fq_e * 4;
; #pragma unroll
;         for (int n = 0; n < 8; ++n) {
;           const int col = nt * 256 + wc_e * 128 + n * 16 + fr_e;
;           if (col < N) epi.r4(g, rig, col, acc[m][n]);
;         }
;       }
	v_mfma_f32_16x16x32_bf16 v[98:101], v[176:179], v[184:187], v[132:135]
	v_ashrrev_i32_e32 v10, 8, v130
	v_add_u32_e32 v10, s5, v10
	v_ashrrev_i32_e32 v11, 31, v10
	v_lshrrev_b32_e32 v11, 28, v11
	v_add_u32_e32 v11, v10, v11
	v_ashrrev_i32_e32 v132, 4, v11
	v_lshlrev_b32_e32 v11, 11, v132
	v_lshlrev_b32_e32 v10, 7, v10
	v_sub_u32_e32 v10, v10, v11
	v_lshrrev_b32_e32 v11, 1, v130
	v_lshrrev_b32_e32 v12, 2, v130
	v_and_b32_e32 v11, 64, v11
	v_and_b32_e32 v12, 12, v12
	v_mfma_f32_16x16x32_bf16 v[42:45], v[216:219], v[180:183], v[164:167]
	v_and_b32_e32 v133, 15, v130
	s_nop 1
	v_or3_b32 v164, v10, v11, v12
	v_mfma_f32_16x16x32_bf16 v[10:13], v[220:223], v[180:183], v[2:5]
	v_ashrrev_i32_e32 v165, 31, v164
	s_nop 1
	v_lshlrev_b32_e32 v2, 1, v130
	v_and_b32_e32 v2, 0x80, v2
	v_mfma_f32_16x16x32_bf16 v[102:105], v[176:179], v[180:183], v[70:73]
	v_or3_b32 v134, v133, v2, s4
	v_ashrrev_i32_e32 v133, 31, v132
	v_lshlrev_b64 v[132:133], 12, v[132:133]
	v_mfma_f32_16x16x32_bf16 v[70:73], v[212:215], v[180:183], v[192:195]
	v_lshl_add_u64 v[132:133], s[20:21], 0, v[132:133]
	v_lshl_add_u64 v[132:133], v[164:165], 1, v[132:133]
	v_cmp_gt_i32_e32 vcc, s30, v134
	v_mfma_f32_16x16x32_bf16 v[66:69], v[212:215], v[184:187], v[34:37]
	v_ashrrev_i32_e32 v135, 31, v134
	v_mfma_f32_16x16x32_bf16 v[34:37], v[216:219], v[184:187], v[168:171]
	v_mfma_f32_16x16x32_bf16 v[2:5], v[220:223], v[184:187], v[172:175]
	v_lshlrev_b32_e32 v236, 2, v134
	global_load_dword v237, v236, s[22:23]
	global_load_dword v238, v236, s[22:23] offset:64
	global_load_dword v239, v236, s[22:23] offset:128
	global_load_dword v240, v236, s[22:23] offset:192
	global_load_dword v241, v236, s[22:23] offset:256
	global_load_dword v242, v236, s[22:23] offset:320
	global_load_dword v243, v236, s[22:23] offset:384
	global_load_dword v244, v236, s[22:23] offset:448
	s_waitcnt vmcnt(0)
	v_lshl_add_u64 v[164:165], v[134:135], 2, s[22:23]
	v_mov_b32_e32 v130, v237
	v_lshlrev_b64 v[164:165], 15, v[134:135]
	v_add_f32_e32 v126, v126, v130
	v_add_f32_e32 v127, v127, v130
	v_add_f32_e32 v128, v128, v130
	v_add_f32_e32 v129, v129, v130
	v_cvt_pk_bf16_f32 v126, v126, v127
	v_cvt_pk_bf16_f32 v127, v128, v129
	v_lshl_add_u64 v[128:129], v[132:133], 0, v[164:165]
	global_store_dwordx2 v[128:129], v[126:127], off
	v_or_b32_e32 v126, 16, v134
	v_ashrrev_i32_e32 v127, 31, v126
	v_lshl_add_u64 v[128:129], v[126:127], 2, s[22:23]
	v_mov_b32_e32 v130, v238
	v_lshlrev_b64 v[128:129], 15, v[126:127]
	v_add_f32_e32 v122, v122, v130
	v_add_f32_e32 v123, v123, v130
	v_add_f32_e32 v124, v124, v130
	v_add_f32_e32 v125, v125, v130
	v_cvt_pk_bf16_f32 v122, v122, v123
	v_cvt_pk_bf16_f32 v123, v124, v125
	v_lshl_add_u64 v[124:125], v[132:133], 0, v[128:129]
	global_store_dwordx2 v[124:125], v[122:123], off
	v_or_b32_e32 v122, 32, v134
	v_ashrrev_i32_e32 v123, 31, v122
	v_lshl_add_u64 v[124:125], v[122:123], 2, s[22:23]
	v_mov_b32_e32 v128, v239
	v_lshlrev_b64 v[124:125], 15, v[122:123]
	v_add_f32_e32 v118, v118, v128
	v_add_f32_e32 v119, v119, v128
	v_add_f32_e32 v120, v120, v128
	v_add_f32_e32 v121, v121, v128
	v_cvt_pk_bf16_f32 v118, v118, v119
	v_cvt_pk_bf16_f32 v119, v120, v121
	v_lshl_add_u64 v[120:121], v[132:133], 0, v[124:125]
	global_store_dwordx2 v[120:121], v[118:119], off
	v_or_b32_e32 v118, 48, v134
	v_ashrrev_i32_e32 v119, 31, v118
	v_lshl_add_u64 v[120:121], v[118:119], 2, s[22:23]
	v_mov_b32_e32 v124, v240
	v_lshlrev_b64 v[120:121], 15, v[118:119]
	v_add_f32_e32 v114, v114, v124
	v_add_f32_e32 v115, v115, v124
	v_add_f32_e32 v116, v116, v124
	v_add_f32_e32 v117, v117, v124
	v_cvt_pk_bf16_f32 v114, v114, v115
	v_cvt_pk_bf16_f32 v115, v116, v117
	v_lshl_add_u64 v[116:117], v[132:133], 0, v[120:121]
	global_store_dwordx2 v[116:117], v[114:115], off
	v_or_b32_e32 v114, 64, v134
	v_ashrrev_i32_e32 v115, 31, v114
	v_lshl_add_u64 v[116:117], v[114:115], 2, s[22:23]
	v_mov_b32_e32 v120, v241
	v_lshlrev_b64 v[116:117], 15, v[114:115]
	v_add_f32_e32 v110, v110, v120
	v_add_f32_e32 v111, v111, v120
	v_add_f32_e32 v112, v112, v120
	v_add_f32_e32 v113, v113, v120
	v_cvt_pk_bf16_f32 v110, v110, v111
	v_cvt_pk_bf16_f32 v111, v112, v113
	v_lshl_add_u64 v[112:113], v[132:133], 0, v[116:117]
	global_store_dwordx2 v[112:113], v[110:111], off
	v_or_b32_e32 v110, 0x50, v134
	v_ashrrev_i32_e32 v111, 31, v110
	v_lshl_add_u64 v[112:113], v[110:111], 2, s[22:23]
	v_mov_b32_e32 v116, v242
	v_lshlrev_b64 v[112:113], 15, v[110:111]
	v_add_f32_e32 v106, v106, v116
	v_add_f32_e32 v107, v107, v116
	v_add_f32_e32 v108, v108, v116
	v_add_f32_e32 v109, v109, v116
	v_cvt_pk_bf16_f32 v106, v106, v107
	v_cvt_pk_bf16_f32 v107, v108, v109
	v_lshl_add_u64 v[108:109], v[132:133], 0, v[112:113]
	global_store_dwordx2 v[108:109], v[106:107], off
	v_or_b32_e32 v106, 0x60, v134
	v_ashrrev_i32_e32 v107, 31, v106
	v_lshl_add_u64 v[108:109], v[106:107], 2, s[22:23]
	v_mov_b32_e32 v112, v243
	v_lshlrev_b64 v[108:109], 15, v[106:107]
	v_add_f32_e32 v102, v102, v112
	v_add_f32_e32 v103, v103, v112
	v_add_f32_e32 v104, v104, v112
	v_add_f32_e32 v105, v105, v112
	v_cvt_pk_bf16_f32 v102, v102, v103
	v_cvt_pk_bf16_f32 v103, v104, v105
	v_lshl_add_u64 v[104:105], v[132:133], 0, v[108:109]
	global_store_dwordx2 v[104:105], v[102:103], off
	v_or_b32_e32 v102, 0x70, v134
	v_ashrrev_i32_e32 v103, 31, v102
	v_lshl_add_u64 v[104:105], v[102:103], 2, s[22:23]
	v_mov_b32_e32 v108, v244
	v_lshlrev_b64 v[104:105], 15, v[102:103]
	v_add_f32_e32 v98, v98, v108
	v_add_f32_e32 v99, v99, v108
	v_add_f32_e32 v100, v100, v108
	v_add_f32_e32 v101, v101, v108
	v_cvt_pk_bf16_f32 v98, v98, v99
	v_cvt_pk_bf16_f32 v99, v100, v101
	v_lshl_add_u64 v[100:101], v[132:133], 0, v[104:105]
; __device__ __forceinline__ unsigned pack2(float a, float b) { unsigned r; asm("v_cvt_pk_bf16_f32 %0, %1, %2" : "=v"(r) : "v"(a), "v"(b)); return r; }
;   __device__ __forceinline__ void r4(int g, int rig, int col, f32x4 v) const {
;     const float b = bias[col];
;     uint2 u; u.x = pack2(v[0] + b, v[1] + b); u.y = pack2(v[2] + b, v[3] + b);
;     *(uint2*)(out + (size_t)col * 16384 + (size_t)g * 2048 + rig) = u;
;   }
; template <bool SWAP, class Epi, bool THIN = false> ...
;     ...
;     } else if constexpr (Epi::KIND == 1) {
; #pragma unroll
;       for (int m = 0; m < 4; ++m) {
;         const int rig = rig0 + rw + m * 16 + fq_e * 4;
; #pragma unroll
;         for (int n = 0; n < 8; ++n) {
;           const int col = nt * 256 + wc_e * 128 + n * 16 + fr_e;
;           if (col < N) epi.r4(g, rig, col, acc[m][n]);
;         }
;       }
	global_store_dwordx2 v[100:101], v[98:99], off
	v_lshl_add_u64 v[98:99], v[134:135], 2, s[22:23]
	v_mov_b32_e32 v100, v237
	v_lshlrev_b64 v[98:99], 15, v[134:135]
	v_add_f32_e32 v94, v94, v100
	v_add_f32_e32 v95, v95, v100
	v_add_f32_e32 v96, v96, v100
	v_add_f32_e32 v97, v97, v100
	v_cvt_pk_bf16_f32 v94, v94, v95
	v_cvt_pk_bf16_f32 v95, v96, v97
	v_lshl_add_u64 v[96:97], v[132:133], 0, v[98:99]
	global_store_dwordx2 v[96:97], v[94:95], off offset:32
	v_lshl_add_u64 v[94:95], v[126:127], 2, s[22:23]
	v_mov_b32_e32 v96, v238
	v_lshlrev_b64 v[94:95], 15, v[126:127]
	v_add_f32_e32 v90, v90, v96
	v_add_f32_e32 v91, v91, v96
	v_add_f32_e32 v92, v92, v96
	v_add_f32_e32 v93, v93, v96
	v_cvt_pk_bf16_f32 v90, v90, v91
	v_cvt_pk_bf16_f32 v91, v92, v93
	v_lshl_add_u64 v[92:93], v[132:133], 0, v[94:95]
	global_store_dwordx2 v[92:93], v[90:91], off offset:32
	v_lshl_add_u64 v[90:91], v[122:123], 2, s[22:23]
	v_mov_b32_e32 v92, v239
	v_lshlrev_b64 v[90:91], 15, v[122:123]
	v_add_f32_e32 v86, v86, v92
	v_add_f32_e32 v87, v87, v92
	v_add_f32_e32 v88, v88, v92
	v_add_f32_e32 v89, v89, v92
	v_cvt_pk_bf16_f32 v86, v86, v87
	v_cvt_pk_bf16_f32 v87, v88, v89
	v_lshl_add_u64 v[88:89], v[132:133], 0, v[90:91]
	global_store_dwordx2 v[88:89], v[86:87], off offset:32
	v_lshl_add_u64 v[86:87], v[118:119], 2, s[22:23]
	v_mov_b32_e32 v88, v240
	v_lshlrev_b64 v[86:87], 15, v[118:119]
	v_add_f32_e32 v82, v82, v88
	v_add_f32_e32 v83, v83, v88
	v_add_f32_e32 v84, v84, v88
	v_add_f32_e32 v85, v85, v88
	v_cvt_pk_bf16_f32 v82, v82, v83
	v_cvt_pk_bf16_f32 v83, v84, v85
	v_lshl_add_u64 v[84:85], v[132:133], 0, v[86:87]
	global_store_dwordx2 v[84:85], v[82:83], off offset:32
	v_lshl_add_u64 v[82:83], v[114:115], 2, s[22:23]
	v_mov_b32_e32 v84, v241
	v_lshlrev_b64 v[82:83], 15, v[114:115]
	v_add_f32_e32 v78, v78, v84
	v_add_f32_e32 v79, v79, v84
	v_add_f32_e32 v80, v80, v84
	v_add_f32_e32 v81, v81, v84
	v_cvt_pk_bf16_f32 v78, v78, v79
	v_cvt_pk_bf16_f32 v79, v80, v81
	v_lshl_add_u64 v[80:81], v[132:133], 0, v[82:83]
	global_store_dwordx2 v[80:81], v[78:79], off offset:32
	v_lshl_add_u64 v[78:79], v[110:111], 2, s[22:23]
	v_mov_b32_e32 v80, v242
	v_lshlrev_b64 v[78:79], 15, v[110:111]
	v_add_f32_e32 v74, v74, v80
	v_add_f32_e32 v75, v75, v80
	v_add_f32_e32 v76, v76, v80
	v_add_f32_e32 v77, v77, v80
	v_cvt_pk_bf16_f32 v74, v74, v75
	v_cvt_pk_bf16_f32 v75, v76, v77
	v_lshl_add_u64 v[76:77], v[132:133], 0, v[78:79]
	global_store_dwordx2 v[76:77], v[74:75], off offset:32
	v_lshl_add_u64 v[74:75], v[106:107], 2, s[22:23]
	v_mov_b32_e32 v76, v243
	v_lshlrev_b64 v[74:75], 15, v[106:107]
	v_add_f32_e32 v70, v70, v76
	v_add_f32_e32 v71, v71, v76
	v_add_f32_e32 v72, v72, v76
	v_add_f32_e32 v73, v73, v76
	v_cvt_pk_bf16_f32 v70, v70, v71
	v_cvt_pk_bf16_f32 v71, v72, v73
	v_lshl_add_u64 v[72:73], v[132:133], 0, v[74:75]
	global_store_dwordx2 v[72:73], v[70:71], off offset:32
	v_lshl_add_u64 v[70:71], v[102:103], 2, s[22:23]
	v_mov_b32_e32 v72, v244
	v_lshlrev_b64 v[70:71], 15, v[102:103]
	v_add_f32_e32 v66, v66, v72
	v_add_f32_e32 v67, v67, v72
	v_add_f32_e32 v68, v68, v72
	v_add_f32_e32 v69, v69, v72
	v_cvt_pk_bf16_f32 v66, v66, v67
	v_cvt_pk_bf16_f32 v67, v68, v69
	v_lshl_add_u64 v[68:69], v[132:133], 0, v[70:71]
	global_store_dwordx2 v[68:69], v[66:67], off offset:32
	v_lshl_add_u64 v[66:67], v[134:135], 2, s[22:23]
	v_mov_b32_e32 v68, v237
	v_lshlrev_b64 v[66:67], 15, v[134:135]
	v_add_f32_e32 v62, v62, v68
	v_add_f32_e32 v63, v63, v68
	v_add_f32_e32 v64, v64, v68
	v_add_f32_e32 v65, v65, v68
	v_cvt_pk_bf16_f32 v62, v62, v63
	v_cvt_pk_bf16_f32 v63, v64, v65
	v_lshl_add_u64 v[64:65], v[132:133], 0, v[66:67]
	global_store_dwordx2 v[64:65], v[62:63], off offset:64
	v_lshl_add_u64 v[62:63], v[126:127], 2, s[22:23]
	v_mov_b32_e32 v64, v238
	v_lshlrev_b64 v[62:63], 15, v[126:127]
	v_add_f32_e32 v58, v58, v64
	v_add_f32_e32 v59, v59, v64
	v_add_f32_e32 v60, v60, v64
	v_add_f32_e32 v61, v61, v64
	v_cvt_pk_bf16_f32 v58, v58, v59
	v_cvt_pk_bf16_f32 v59, v60, v61
	v_lshl_add_u64 v[60:61], v[132:133], 0, v[62:63]
	global_store_dwordx2 v[60:61], v[58:59], off offset:64
	v_lshl_add_u64 v[58:59], v[122:123], 2, s[22:23]
	v_mov_b32_e32 v60, v239
	v_lshlrev_b64 v[58:59], 15, v[122:123]
	v_add_f32_e32 v54, v54, v60
	v_add_f32_e32 v55, v55, v60
	v_add_f32_e32 v56, v56, v60
	v_add_f32_e32 v57, v57, v60
	v_cvt_pk_bf16_f32 v54, v54, v55
	v_cvt_pk_bf16_f32 v55, v56, v57
	v_lshl_add_u64 v[56:57], v[132:133], 0, v[58:59]
	global_store_dwordx2 v[56:57], v[54:55], off offset:64
	v_lshl_add_u64 v[54:55], v[118:119], 2, s[22:23]
	v_mov_b32_e32 v56, v240
	v_lshlrev_b64 v[54:55], 15, v[118:119]
	v_add_f32_e32 v50, v50, v56
	v_add_f32_e32 v51, v51, v56
	v_add_f32_e32 v52, v52, v56
	v_add_f32_e32 v53, v53, v56
	v_cvt_pk_bf16_f32 v50, v50, v51
	v_cvt_pk_bf16_f32 v51, v52, v53
	v_lshl_add_u64 v[52:53], v[132:133], 0, v[54:55]
; __device__ __forceinline__ unsigned pack2(float a, float b) { unsigned r; asm("v_cvt_pk_bf16_f32 %0, %1, %2" : "=v"(r) : "v"(a), "v"(b)); return r; }
;   __device__ __forceinline__ void r4(int g, int rig, int col, f32x4 v) const {
;     const float b = bias[col];
;     uint2 u; u.x = pack2(v[0] + b, v[1] + b); u.y = pack2(v[2] + b, v[3] + b);
;     *(uint2*)(out + (size_t)col * 16384 + (size_t)g * 2048 + rig) = u;
;   }
; template <bool SWAP, class Epi, bool THIN = false> ...
;     ...
;     } else if constexpr (Epi::KIND == 1) {
; #pragma unroll
;       for (int m = 0; m < 4; ++m) {
;         const int rig = rig0 + rw + m * 16 + fq_e * 4;
; #pragma unroll
;         for (int n = 0; n < 8; ++n) {
;           const int col = nt * 256 + wc_e * 128 + n * 16 + fr_e;
;           if (col < N) epi.r4(g, rig, col, acc[m][n]);
;         }
;       }
	global_store_dwordx2 v[52:53], v[50:51], off offset:64
	v_lshl_add_u64 v[50:51], v[114:115], 2, s[22:23]
	v_mov_b32_e32 v52, v241
	v_lshlrev_b64 v[50:51], 15, v[114:115]
	v_add_f32_e32 v46, v46, v52
	v_add_f32_e32 v47, v47, v52
	v_add_f32_e32 v48, v48, v52
	v_add_f32_e32 v49, v49, v52
	v_cvt_pk_bf16_f32 v46, v46, v47
	v_cvt_pk_bf16_f32 v47, v48, v49
	v_lshl_add_u64 v[48:49], v[132:133], 0, v[50:51]
	global_store_dwordx2 v[48:49], v[46:47], off offset:64
	v_lshl_add_u64 v[46:47], v[110:111], 2, s[22:23]
	v_mov_b32_e32 v48, v242
	v_lshlrev_b64 v[46:47], 15, v[110:111]
	v_add_f32_e32 v38, v38, v48
	v_add_f32_e32 v39, v39, v48
	v_add_f32_e32 v40, v40, v48
	v_add_f32_e32 v41, v41, v48
	v_cvt_pk_bf16_f32 v38, v38, v39
	v_cvt_pk_bf16_f32 v39, v40, v41
	v_lshl_add_u64 v[40:41], v[132:133], 0, v[46:47]
	global_store_dwordx2 v[40:41], v[38:39], off offset:64
	v_lshl_add_u64 v[38:39], v[106:107], 2, s[22:23]
	v_mov_b32_e32 v40, v243
	v_lshlrev_b64 v[38:39], 15, v[106:107]
	v_lshl_add_u64 v[38:39], v[132:133], 0, v[38:39]
	v_add_f32_e32 v41, v42, v40
	v_add_f32_e32 v42, v43, v40
	v_add_f32_e32 v43, v44, v40
	v_add_f32_e32 v44, v45, v40
	v_cvt_pk_bf16_f32 v40, v41, v42
	v_cvt_pk_bf16_f32 v41, v43, v44
	global_store_dwordx2 v[38:39], v[40:41], off offset:64
	v_lshl_add_u64 v[38:39], v[102:103], 2, s[22:23]
	v_mov_b32_e32 v40, v244
	v_lshlrev_b64 v[38:39], 15, v[102:103]
	v_add_f32_e32 v34, v34, v40
	v_add_f32_e32 v35, v35, v40
	v_add_f32_e32 v36, v36, v40
	v_add_f32_e32 v37, v37, v40
	v_cvt_pk_bf16_f32 v34, v34, v35
	v_cvt_pk_bf16_f32 v35, v36, v37
	v_lshl_add_u64 v[36:37], v[132:133], 0, v[38:39]
	global_store_dwordx2 v[36:37], v[34:35], off offset:64
	v_lshl_add_u64 v[34:35], v[134:135], 2, s[22:23]
	v_mov_b32_e32 v36, v237
	v_lshlrev_b64 v[34:35], 15, v[134:135]
	v_add_f32_e32 v30, v30, v36
	v_add_f32_e32 v31, v31, v36
	v_add_f32_e32 v32, v32, v36
	v_add_f32_e32 v33, v33, v36
	v_cvt_pk_bf16_f32 v30, v30, v31
	v_cvt_pk_bf16_f32 v31, v32, v33
	v_lshl_add_u64 v[32:33], v[132:133], 0, v[34:35]
	global_store_dwordx2 v[32:33], v[30:31], off offset:96
	v_lshl_add_u64 v[30:31], v[126:127], 2, s[22:23]
	v_mov_b32_e32 v32, v238
	v_lshlrev_b64 v[30:31], 15, v[126:127]
	v_add_f32_e32 v26, v26, v32
	v_add_f32_e32 v27, v27, v32
	v_add_f32_e32 v28, v28, v32
	v_add_f32_e32 v29, v29, v32
	v_cvt_pk_bf16_f32 v26, v26, v27
	v_cvt_pk_bf16_f32 v27, v28, v29
	v_lshl_add_u64 v[28:29], v[132:133], 0, v[30:31]
	global_store_dwordx2 v[28:29], v[26:27], off offset:96
	v_lshl_add_u64 v[26:27], v[122:123], 2, s[22:23]
	v_mov_b32_e32 v28, v239
	v_lshlrev_b64 v[26:27], 15, v[122:123]
	v_add_f32_e32 v22, v22, v28
	v_add_f32_e32 v23, v23, v28
	v_add_f32_e32 v24, v24, v28
	v_add_f32_e32 v25, v25, v28
	v_cvt_pk_bf16_f32 v22, v22, v23
	v_cvt_pk_bf16_f32 v23, v24, v25
	v_lshl_add_u64 v[24:25], v[132:133], 0, v[26:27]
	global_store_dwordx2 v[24:25], v[22:23], off offset:96
	v_lshl_add_u64 v[22:23], v[118:119], 2, s[22:23]
	v_mov_b32_e32 v24, v240
	v_lshlrev_b64 v[22:23], 15, v[118:119]
	v_add_f32_e32 v18, v18, v24
	v_add_f32_e32 v19, v19, v24
	v_add_f32_e32 v20, v20, v24
	v_add_f32_e32 v21, v21, v24
	v_cvt_pk_bf16_f32 v18, v18, v19
	v_cvt_pk_bf16_f32 v19, v20, v21
	v_lshl_add_u64 v[20:21], v[132:133], 0, v[22:23]
	global_store_dwordx2 v[20:21], v[18:19], off offset:96
	v_lshl_add_u64 v[18:19], v[114:115], 2, s[22:23]
	v_mov_b32_e32 v20, v241
	v_lshlrev_b64 v[18:19], 15, v[114:115]
	v_add_f32_e32 v14, v14, v20
	v_add_f32_e32 v15, v15, v20
	v_add_f32_e32 v16, v16, v20
	v_add_f32_e32 v17, v17, v20
	v_cvt_pk_bf16_f32 v14, v14, v15
	v_cvt_pk_bf16_f32 v15, v16, v17
	v_lshl_add_u64 v[16:17], v[132:133], 0, v[18:19]
	global_store_dwordx2 v[16:17], v[14:15], off offset:96
	v_lshl_add_u64 v[14:15], v[110:111], 2, s[22:23]
	v_mov_b32_e32 v16, v242
	v_lshlrev_b64 v[14:15], 15, v[110:111]
	v_add_f32_e32 v6, v6, v16
	v_add_f32_e32 v7, v7, v16
	v_add_f32_e32 v8, v8, v16
	v_add_f32_e32 v9, v9, v16
	v_cvt_pk_bf16_f32 v6, v6, v7
	v_cvt_pk_bf16_f32 v7, v8, v9
	v_lshl_add_u64 v[8:9], v[132:133], 0, v[14:15]
	global_store_dwordx2 v[8:9], v[6:7], off offset:96
	v_lshl_add_u64 v[6:7], v[106:107], 2, s[22:23]
	v_mov_b32_e32 v8, v243
	v_lshlrev_b64 v[6:7], 15, v[106:107]
	v_lshl_add_u64 v[6:7], v[132:133], 0, v[6:7]
	v_add_f32_e32 v9, v10, v8
	v_add_f32_e32 v10, v11, v8
	v_add_f32_e32 v11, v12, v8
	v_add_f32_e32 v12, v13, v8
	v_cvt_pk_bf16_f32 v8, v9, v10
	v_cvt_pk_bf16_f32 v9, v11, v12
	global_store_dwordx2 v[6:7], v[8:9], off offset:96
	v_lshl_add_u64 v[6:7], v[102:103], 2, s[22:23]
	v_mov_b32_e32 v8, v244
	v_lshlrev_b64 v[6:7], 15, v[102:103]
	v_add_f32_e32 v2, v2, v8
	v_add_f32_e32 v3, v3, v8
	v_add_f32_e32 v4, v4, v8
	v_add_f32_e32 v5, v5, v8
	v_cvt_pk_bf16_f32 v2, v2, v3
	v_cvt_pk_bf16_f32 v3, v4, v5
	v_lshl_add_u64 v[4:5], v[132:133], 0, v[6:7]
	global_store_dwordx2 v[4:5], v[2:3], off offset:96
	s_branch .LBB0_2712
